# P5: gg/Rb loads of the second half hoisted before the drain, later waits neutralised (no more per-step store-ack waits)
# speedup vs baseline: 1.0548x; 1.0025x over previous
; __device__ __forceinline__ f32x4 ld_bf4(const bf16_t* p) { u32x2 w = *(const u32x2*)p; return (f32x4){__uint_as_float(w.x << 16), __uint_as_float(w.x & 0xffff0000u), __uint_as_float(w.y << 16), __uint_as_float(w.y & 0xffff0000u)}; }
; __global__ void __launch_bounds__(NTHR, 2) fwd_kernel(Args a) {
;     ...
;     for (int it = 0; it < (G == 256 ? 1 : 0); ++it) { const int lt = (bx >> 3) * 8 + wave, bhx = 2 * (bx & 7) + (lt >> 7), h = bhx & 3, b = bhx >> 2, n = (lt >> 2) & 31, ct = lt & 3, fr = lane & 15, fq = lane >> 4;
;         f32x4 ov[16]; float ss = 0.f;
; #pragma unroll
;         for (int t = 0; t < 16; ++t) { const size_t o = ((((((size_t)(b * 32 + n) * 4 + h) * 8 + (t >> 1)) * 4 + ct) * 2 + (t & 1)) * 64 + lane) << 2;
;             const f32x4 x = ld_bf4(Of + o) + ld_bf4(Ob + o); ov[t] = x; ss += (x[0] * x[0] + x[1] * x[1]) + (x[2] * x[2] + x[3] * x[3]); }
.LBB0_1343:
	v_readlane_b32 s2, v254, 54
	v_mov_b32_e32 v0, v189
	v_readlane_b32 s3, v254, 55
	s_andn2_b64 vcc, exec, s[2:3]
	v_readfirstlane_b32 s2, v0
	s_cbranch_vccnz .LBB0_1345
	s_ashr_i32 s2, s2, 6
	s_and_b32 s3, s88, -8
	s_add_i32 s3, s2, s3
	s_lshl_b32 s4, s33, 1
	s_ashr_i32 s5, s3, 7
	s_add_i32 s5, s5, s4
	s_ashr_i32 s7, s5, 2
	s_bfe_u32 s3, s3, 0x50002
	s_and_b32 s8, s2, 3
	s_lshl_b32 s2, s7, 5
	s_or_b32 s4, s2, s3
	s_lshl_b32 s2, s7, 11
	s_lshl_b32 s3, s3, 6
	v_readlane_b32 s12, v254, 17
	s_and_b32 s6, s5, 3
	s_or_b32 s2, s2, s3
	s_lshl_b32 s3, s8, 4
	v_readlane_b32 s13, v254, 18
	v_readlane_b32 s20, v254, 25
	v_readlane_b32 s21, v254, 26
	s_ashr_i32 s5, s4, 31
	s_or_b32 s7, s2, s3
	s_lshl_b32 s9, s6, 8
	s_lshl_b32 s2, s6, 10
	s_mov_b64 s[12:13], s[20:21]
	s_add_u32 s2, s12, s2
	s_addc_u32 s3, s13, 0
	s_lshl_b64 s[4:5], s[4:5], 17
	s_lshl_b32 s6, s6, 15
	s_or_b32 s4, s4, s6
	s_lshl_b32 s6, s8, 10
	v_lshlrev_b32_e32 v1, 3, v0
	s_or_b32 s4, s4, s6
	v_and_b32_e32 v1, 0x1f8, v1
	s_waitcnt vmcnt(18)
	v_or_b32_e32 v22, s4, v1
	v_mov_b32_e32 v23, s5
	v_lshl_add_u64 v[2:3], s[82:83], 0, v[22:23]
	v_lshl_add_u64 v[4:5], s[80:81], 0, v[22:23]
	global_load_dwordx2 v[2:3], v[2:3], off
	v_or_b32_e32 v6, 0x200, v22
	global_load_dwordx2 v[4:5], v[4:5], off
	v_mov_b32_e32 v7, s5
	s_waitcnt vmcnt(17) lgkmcnt(0)
	v_lshl_add_u64 v[8:9], s[82:83], 0, v[6:7]
	v_lshl_add_u64 v[6:7], s[80:81], 0, v[6:7]
	global_load_dwordx2 v[8:9], v[8:9], off
	v_mov_b32_e32 v11, s5
	global_load_dwordx2 v[6:7], v[6:7], off
	v_or_b32_e32 v10, 0x1000, v22
	v_mov_b32_e32 v15, s5
	v_or_b32_e32 v14, 0x1200, v22
	v_lshl_add_u64 v[12:13], s[82:83], 0, v[10:11]
	v_lshl_add_u64 v[10:11], s[80:81], 0, v[10:11]
	v_lshl_add_u64 v[16:17], s[82:83], 0, v[14:15]
	v_lshl_add_u64 v[14:15], s[80:81], 0, v[14:15]
	global_load_dwordx2 v[12:13], v[12:13], off
	v_mbcnt_lo_u32_b32 v1, -1, 0
	global_load_dwordx2 v[16:17], v[16:17], off
	s_waitcnt vmcnt(8)
	v_mbcnt_hi_u32_b32 v68, -1, v1
	global_load_dwordx2 v[14:15], v[14:15], off
	v_and_b32_e32 v19, 64, v68
	global_load_dwordx2 v[10:11], v[10:11], off
	v_xor_b32_e32 v18, 16, v68
	v_add_u32_e32 v70, 64, v19
	v_lshrrev_b32_e32 v1, 2, v0
	v_cmp_lt_i32_e32 vcc, v18, v70
	v_and_b32_e32 v20, 12, v1
	v_mov_b32_e32 v19, s5
	v_cndmask_b32_e32 v1, v68, v18, vcc
	v_or_b32_e32 v18, 0x2000, v22
	v_lshl_add_u64 v[26:27], s[82:83], 0, v[18:19]
	v_lshl_add_u64 v[18:19], s[80:81], 0, v[18:19]
	global_load_dwordx2 v[26:27], v[26:27], off
	s_nop 0
	global_load_dwordx2 v[30:31], v[18:19], off
	v_and_or_b32 v0, v0, 15, s7
	v_lshlrev_b32_e32 v71, 2, v1
	v_ashrrev_i32_e32 v1, 31, v0
	v_lshlrev_b64 v[0:1], 10, v[0:1]
	v_or3_b32 v0, v0, s9, v20
	v_mov_b32_e32 v21, s5
	v_readlane_b32 s4, v254, 42
	v_lshlrev_b32_e32 v69, 2, v20
	v_lshlrev_b64 v[24:25], 1, v[0:1]
	v_readlane_b32 s5, v254, 43
	v_or_b32_e32 v20, 0x2200, v22
	v_lshl_add_u64 v[28:29], s[82:83], 0, v[20:21]
	v_lshl_add_u64 v[0:1], s[4:5], 0, v[24:25]
	global_load_dwordx2 v[28:29], v[28:29], off
	s_mov_b32 s4, 0x800000
	v_lshl_add_u64 v[24:25], s[0:1], 0, v[24:25]
	v_readlane_b32 s14, v254, 19
	v_readlane_b32 s15, v254, 20
	v_readlane_b32 s16, v254, 21
	v_readlane_b32 s17, v254, 22
	v_readlane_b32 s18, v254, 23
	v_readlane_b32 s19, v254, 24
	v_readlane_b32 s22, v254, 27
	v_readlane_b32 s23, v254, 28
	v_readlane_b32 s24, v254, 29
	v_readlane_b32 s25, v254, 30
	v_readlane_b32 s26, v254, 31
	v_readlane_b32 s27, v254, 32
	global_load_dwordx2 v[86:87], v[0:1], off
	s_waitcnt vmcnt(11)
	v_lshlrev_b32_e32 v18, 16, v2
	v_and_b32_e32 v19, 0xffff0000, v2
	v_lshlrev_b32_e32 v32, 16, v3
	v_and_b32_e32 v33, 0xffff0000, v3
	s_waitcnt vmcnt(10)
	v_lshlrev_b32_e32 v2, 16, v4
	v_and_b32_e32 v3, 0xffff0000, v4
	v_lshlrev_b32_e32 v4, 16, v5
	v_and_b32_e32 v5, 0xffff0000, v5
	v_pk_add_f32 v[2:3], v[18:19], v[2:3]
	v_pk_add_f32 v[4:5], v[32:33], v[4:5]
	v_pk_mul_f32 v[36:37], v[2:3], v[2:3]
	v_pk_mul_f32 v[34:35], v[4:5], v[4:5]
	s_waitcnt vmcnt(9)
	v_lshlrev_b32_e32 v18, 16, v8
	v_pk_mov_b32 v[38:39], v[36:37], v[34:35] op_sel:[1,0]
	v_mov_b32_e32 v37, v35
	v_and_b32_e32 v19, 0xffff0000, v8
	v_lshlrev_b32_e32 v8, 16, v9
	v_and_b32_e32 v9, 0xffff0000, v9
	s_waitcnt vmcnt(8)
	v_lshlrev_b32_e32 v32, 16, v6
	v_and_b32_e32 v33, 0xffff0000, v6
	v_pk_add_f32 v[34:35], v[38:39], v[36:37]
	v_lshlrev_b32_e32 v36, 16, v7
	v_and_b32_e32 v37, 0xffff0000, v7
	v_pk_add_f32 v[6:7], v[18:19], v[32:33]
	v_pk_add_f32 v[8:9], v[8:9], v[36:37]
	v_pk_mul_f32 v[32:33], v[6:7], v[6:7]
	v_pk_mul_f32 v[18:19], v[8:9], v[8:9]
	s_waitcnt vmcnt(4)
	v_lshlrev_b32_e32 v40, 16, v10
	v_pk_mov_b32 v[36:37], v[32:33], v[18:19] op_sel:[1,0]
	v_mov_b32_e32 v33, v19
	v_lshl_add_u64 v[18:19], s[80:81], 0, v[20:21]
	global_load_dwordx2 v[38:39], v[18:19], off
	v_or_b32_e32 v18, 0x3000, v22
	v_mov_b32_e32 v19, v23
	v_pk_add_f32 v[32:33], v[36:37], v[32:33]
	v_lshl_add_u64 v[36:37], s[82:83], 0, v[18:19]
	v_lshl_add_u64 v[18:19], s[80:81], 0, v[18:19]
	global_load_dwordx2 v[36:37], v[36:37], off
	v_lshlrev_b32_e32 v20, 16, v12
	global_load_dwordx2 v[42:43], v[18:19], off
	v_and_b32_e32 v21, 0xffff0000, v12
	v_lshlrev_b32_e32 v12, 16, v13
	v_and_b32_e32 v13, 0xffff0000, v13
	v_and_b32_e32 v41, 0xffff0000, v10
	v_lshlrev_b32_e32 v10, 16, v11
	v_and_b32_e32 v11, 0xffff0000, v11
	v_pk_add_f32 v[18:19], v[12:13], v[10:11]
	v_lshlrev_b32_e32 v12, 16, v16
	v_and_b32_e32 v13, 0xffff0000, v16
	v_lshlrev_b32_e32 v10, 16, v17
	v_and_b32_e32 v11, 0xffff0000, v17
	v_lshlrev_b32_e32 v16, 16, v14
	v_and_b32_e32 v17, 0xffff0000, v14
	v_lshlrev_b32_e32 v14, 16, v15
	v_and_b32_e32 v15, 0xffff0000, v15
	v_pk_add_f32 v[12:13], v[12:13], v[16:17]
	v_pk_add_f32 v[10:11], v[10:11], v[14:15]
	v_mul_f32_e32 v16, v12, v12
	v_pk_add_f32 v[14:15], v[34:35], v[34:35] op_sel:[0,1] op_sel_hi:[1,0]
	v_pk_add_f32 v[20:21], v[20:21], v[40:41]
	v_mov_b32_e32 v15, v16
	v_pk_add_f32 v[16:17], v[32:33], v[32:33] op_sel:[0,1] op_sel_hi:[1,0]
	v_or_b32_e32 v32, 0x3200, v22
	v_mov_b32_e32 v33, v23
	v_mul_f32_e32 v40, v13, v13
	v_lshl_add_u64 v[34:35], s[82:83], 0, v[32:33]
	v_lshl_add_u64 v[32:33], s[80:81], 0, v[32:33]
	v_mov_b32_e32 v17, v40
	global_load_dwordx2 v[34:35], v[34:35], off
	v_pk_add_f32 v[14:15], v[14:15], v[16:17]
	global_load_dwordx2 v[40:41], v[32:33], off
	v_mul_f32_e32 v16, v21, v21
	v_mul_f32_e32 v32, v19, v19
	v_mul_f32_e32 v44, v10, v10
	v_mul_f32_e32 v45, v11, v11
	v_pk_fma_f32 v[16:17], v[20:21], v[20:21], v[16:17] op_sel_hi:[1,1,0]
	v_pk_fma_f32 v[32:33], v[18:19], v[18:19], v[32:33] op_sel_hi:[1,1,0]
	v_mov_b32_e32 v17, v44
	v_mov_b32_e32 v33, v45
	v_pk_add_f32 v[16:17], v[16:17], v[32:33]
	v_or_b32_e32 v32, 0x4000, v22
	v_pk_add_f32 v[44:45], v[14:15], v[16:17]
	s_waitcnt vmcnt(8)
; __device__ __forceinline__ f32x4 ld_bf4(const bf16_t* p) { u32x2 w = *(const u32x2*)p; return (f32x4){__uint_as_float(w.x << 16), __uint_as_float(w.x & 0xffff0000u), __uint_as_float(w.y << 16), __uint_as_float(w.y & 0xffff0000u)}; }
; __global__ void __launch_bounds__(NTHR, 2) fwd_kernel(Args a) {
;     ...
;         for (int t = 0; t < 16; ++t) { const size_t o = ((((((size_t)(b * 32 + n) * 4 + h) * 8 + (t >> 1)) * 4 + ct) * 2 + (t & 1)) * 64 + lane) << 2;
;             const f32x4 x = ld_bf4(Of + o) + ld_bf4(Ob + o); ov[t] = x; ss += (x[0] * x[0] + x[1] * x[1]) + (x[2] * x[2] + x[3] * x[3]); }
	v_lshlrev_b32_e32 v14, 16, v26
	v_and_b32_e32 v15, 0xffff0000, v26
	v_lshlrev_b32_e32 v16, 16, v27
	v_and_b32_e32 v17, 0xffff0000, v27
	s_waitcnt vmcnt(7)
	v_lshlrev_b32_e32 v26, 16, v30
	v_and_b32_e32 v27, 0xffff0000, v30
	v_lshlrev_b32_e32 v30, 16, v31
	v_and_b32_e32 v31, 0xffff0000, v31
	v_pk_add_f32 v[14:15], v[14:15], v[26:27]
	v_pk_add_f32 v[16:17], v[16:17], v[30:31]
	v_pk_mul_f32 v[30:31], v[14:15], v[14:15]
	v_pk_mul_f32 v[26:27], v[16:17], v[16:17]
	v_mov_b32_e32 v33, v23
	v_pk_mov_b32 v[48:49], v[30:31], v[26:27] op_sel:[1,0]
	v_mov_b32_e32 v31, v27
	v_pk_add_f32 v[48:49], v[48:49], v[30:31]
	v_lshl_add_u64 v[30:31], s[80:81], 0, v[32:33]
	v_lshl_add_u64 v[46:47], s[82:83], 0, v[32:33]
	global_load_dwordx2 v[50:51], v[30:31], off
	v_or_b32_e32 v30, 0x4200, v22
	v_mov_b32_e32 v31, v23
	global_load_dwordx2 v[46:47], v[46:47], off
	v_lshl_add_u64 v[32:33], s[82:83], 0, v[30:31]
	v_lshl_add_u64 v[30:31], s[80:81], 0, v[30:31]
	global_load_dwordx2 v[52:53], v[32:33], off
	global_load_dwordx2 v[54:55], v[30:31], off
	s_waitcnt vmcnt(10)
	v_lshlrev_b32_e32 v26, 16, v28
	v_and_b32_e32 v27, 0xffff0000, v28
	v_lshlrev_b32_e32 v28, 16, v29
	v_and_b32_e32 v29, 0xffff0000, v29
	s_waitcnt vmcnt(8)
	v_lshlrev_b32_e32 v32, 16, v38
	v_and_b32_e32 v33, 0xffff0000, v38
	v_lshlrev_b32_e32 v30, 16, v39
	v_and_b32_e32 v31, 0xffff0000, v39
	v_pk_add_f32 v[30:31], v[28:29], v[30:31]
	v_pk_add_f32 v[32:33], v[26:27], v[32:33]
	s_waitcnt vmcnt(7)
	v_lshlrev_b32_e32 v28, 16, v36
	v_and_b32_e32 v29, 0xffff0000, v36
	v_lshlrev_b32_e32 v26, 16, v37
	v_and_b32_e32 v27, 0xffff0000, v37
	s_waitcnt vmcnt(6)
	v_lshlrev_b32_e32 v36, 16, v42
	v_and_b32_e32 v37, 0xffff0000, v42
	v_lshlrev_b32_e32 v38, 16, v43
	v_and_b32_e32 v39, 0xffff0000, v43
	v_pk_add_f32 v[28:29], v[28:29], v[36:37]
	v_pk_add_f32 v[26:27], v[26:27], v[38:39]
	v_mul_f32_e32 v38, v28, v28
	v_pk_add_f32 v[36:37], v[44:45], v[44:45] op_sel:[0,1] op_sel_hi:[1,0]
	v_mul_f32_e32 v42, v29, v29
	v_mov_b32_e32 v37, v38
	v_pk_add_f32 v[38:39], v[48:49], v[48:49] op_sel:[0,1] op_sel_hi:[1,0]
	v_mul_f32_e32 v43, v26, v26
	v_mov_b32_e32 v39, v42
	v_pk_add_f32 v[36:37], v[36:37], v[38:39]
	v_mul_f32_e32 v38, v33, v33
	v_pk_fma_f32 v[38:39], v[32:33], v[32:33], v[38:39] op_sel_hi:[1,1,0]
	v_mul_f32_e32 v42, v31, v31
	v_mul_f32_e32 v56, v27, v27
	v_mov_b32_e32 v39, v43
	v_pk_fma_f32 v[42:43], v[30:31], v[30:31], v[42:43] op_sel_hi:[1,1,0]
	s_nop 0
	v_mov_b32_e32 v43, v56
	v_pk_add_f32 v[38:39], v[38:39], v[42:43]
	v_or_b32_e32 v42, 0x5000, v22
	v_mov_b32_e32 v43, v23
	v_lshl_add_u64 v[44:45], s[82:83], 0, v[42:43]
	v_pk_add_f32 v[56:57], v[36:37], v[38:39]
	s_waitcnt vmcnt(5)
	v_lshlrev_b32_e32 v36, 16, v34
	v_and_b32_e32 v37, 0xffff0000, v34
	v_lshlrev_b32_e32 v34, 16, v35
	v_and_b32_e32 v35, 0xffff0000, v35
	s_waitcnt vmcnt(4)
	v_lshlrev_b32_e32 v38, 16, v40
	v_and_b32_e32 v39, 0xffff0000, v40
	v_lshl_add_u64 v[42:43], s[80:81], 0, v[42:43]
	v_lshlrev_b32_e32 v40, 16, v41
	v_and_b32_e32 v41, 0xffff0000, v41
	global_load_dwordx2 v[48:49], v[44:45], off
	global_load_dwordx2 v[58:59], v[42:43], off
	v_pk_add_f32 v[42:43], v[36:37], v[38:39]
	v_pk_add_f32 v[44:45], v[34:35], v[40:41]
	v_pk_mul_f32 v[36:37], v[42:43], v[42:43]
	v_pk_mul_f32 v[34:35], v[44:45], v[44:45]
	v_or_b32_e32 v40, 0x5200, v22
	v_pk_mov_b32 v[38:39], v[36:37], v[34:35] op_sel:[1,0]
	v_mov_b32_e32 v41, v23
	v_mov_b32_e32 v37, v35
	v_lshl_add_u64 v[60:61], s[82:83], 0, v[40:41]
	v_pk_add_f32 v[62:63], v[38:39], v[36:37]
	v_lshl_add_u64 v[34:35], s[80:81], 0, v[40:41]
	v_or_b32_e32 v36, 0x6000, v22
	v_mov_b32_e32 v37, v23
	global_load_dwordx2 v[60:61], v[60:61], off
	v_lshl_add_u64 v[38:39], s[82:83], 0, v[36:37]
	global_load_dwordx2 v[72:73], v[34:35], off
	global_load_dwordx2 v[74:75], v[38:39], off
	v_lshl_add_u64 v[36:37], s[80:81], 0, v[36:37]
	s_waitcnt vmcnt(8)
	v_lshlrev_b32_e32 v40, 16, v51
	v_and_b32_e32 v41, 0xffff0000, v51
	s_waitcnt vmcnt(7)
	v_lshlrev_b32_e32 v34, 16, v46
	v_and_b32_e32 v35, 0xffff0000, v46
	v_lshlrev_b32_e32 v38, 16, v47
	v_and_b32_e32 v39, 0xffff0000, v47
	global_load_dwordx2 v[46:47], v[36:37], off
	v_lshlrev_b32_e32 v36, 16, v50
	v_and_b32_e32 v37, 0xffff0000, v50
	v_pk_add_f32 v[38:39], v[38:39], v[40:41]
	v_pk_add_f32 v[40:41], v[34:35], v[36:37]
	s_waitcnt vmcnt(7)
	v_lshlrev_b32_e32 v36, 16, v52
	v_and_b32_e32 v37, 0xffff0000, v52
	s_waitcnt vmcnt(6)
	v_lshlrev_b32_e32 v50, 16, v54
	v_and_b32_e32 v51, 0xffff0000, v54
	v_pk_add_f32 v[36:37], v[36:37], v[50:51]
	v_lshlrev_b32_e32 v34, 16, v53
	v_and_b32_e32 v35, 0xffff0000, v53
	v_lshlrev_b32_e32 v52, 16, v55
	v_and_b32_e32 v53, 0xffff0000, v55
	v_mul_f32_e32 v64, v36, v36
	v_mul_f32_e32 v65, v37, v37
	v_pk_add_f32 v[54:55], v[56:57], v[56:57] op_sel:[0,1] op_sel_hi:[1,0]
	v_pk_add_f32 v[56:57], v[62:63], v[62:63] op_sel:[0,1] op_sel_hi:[1,0]
	v_mov_b32_e32 v55, v64
	v_mov_b32_e32 v57, v65
	v_pk_add_f32 v[34:35], v[34:35], v[52:53]
	v_pk_add_f32 v[54:55], v[54:55], v[56:57]
	v_mul_f32_e32 v56, v41, v41
	v_mul_f32_e32 v62, v39, v39
	v_mul_f32_e32 v66, v34, v34
	v_mul_f32_e32 v78, v35, v35
	v_pk_fma_f32 v[56:57], v[40:41], v[40:41], v[56:57] op_sel_hi:[1,1,0]
	v_pk_fma_f32 v[62:63], v[38:39], v[38:39], v[62:63] op_sel_hi:[1,1,0]
	v_or_b32_e32 v50, 0x6200, v22
	v_mov_b32_e32 v51, v23
	v_mov_b32_e32 v57, v66
	v_or_b32_e32 v64, 0x7000, v22
	v_mov_b32_e32 v65, v23
	v_mov_b32_e32 v63, v78
	v_lshl_add_u64 v[52:53], s[82:83], 0, v[50:51]
	v_lshl_add_u64 v[50:51], s[80:81], 0, v[50:51]
	v_pk_add_f32 v[56:57], v[56:57], v[62:63]
	v_lshl_add_u64 v[62:63], s[80:81], 0, v[64:65]
	global_load_dwordx2 v[52:53], v[52:53], off
	v_lshl_add_u64 v[66:67], s[82:83], 0, v[64:65]
	global_load_dwordx2 v[78:79], v[62:63], off
	v_or_b32_e32 v22, 0x7200, v22
	global_load_dwordx2 v[50:51], v[50:51], off
	v_lshl_add_u64 v[62:63], s[82:83], 0, v[22:23]
	global_load_dwordx2 v[76:77], v[66:67], off
	global_load_dwordx2 v[80:81], v[62:63], off
	v_lshl_add_u64 v[22:23], s[80:81], 0, v[22:23]
	global_load_dwordx2 v[82:83], v[22:23], off
	v_pk_add_f32 v[54:55], v[54:55], v[56:57]
	s_waitcnt vmcnt(11)
; __device__ __forceinline__ f32x4 ld_bf4(const bf16_t* p) { u32x2 w = *(const u32x2*)p; return (f32x4){__uint_as_float(w.x << 16), __uint_as_float(w.x & 0xffff0000u), __uint_as_float(w.y << 16), __uint_as_float(w.y & 0xffff0000u)}; }
; __global__ void __launch_bounds__(NTHR, 2) fwd_kernel(Args a) {
;     ...
;         for (int t = 0; t < 16; ++t) { const size_t o = ((((((size_t)(b * 32 + n) * 4 + h) * 8 + (t >> 1)) * 4 + ct) * 2 + (t & 1)) * 64 + lane) << 2;
;             const f32x4 x = ld_bf4(Of + o) + ld_bf4(Ob + o); ov[t] = x; ss += (x[0] * x[0] + x[1] * x[1]) + (x[2] * x[2] + x[3] * x[3]); }
;         ss += __shfl_xor(ss, 16); ss += __shfl_xor(ss, 32);
	v_lshlrev_b32_e32 v56, 16, v48
	v_and_b32_e32 v57, 0xffff0000, v48
	v_lshlrev_b32_e32 v48, 16, v49
	v_and_b32_e32 v49, 0xffff0000, v49
	s_waitcnt vmcnt(10)
	v_lshlrev_b32_e32 v22, 16, v58
	v_and_b32_e32 v23, 0xffff0000, v58
	v_lshlrev_b32_e32 v58, 16, v59
	v_and_b32_e32 v59, 0xffff0000, v59
	v_pk_add_f32 v[64:65], v[56:57], v[22:23]
	v_pk_add_f32 v[66:67], v[48:49], v[58:59]
	v_pk_mul_f32 v[48:49], v[64:65], v[64:65]
	v_pk_mul_f32 v[22:23], v[66:67], v[66:67]
	v_pk_add_f32 v[54:55], v[54:55], v[54:55] op_sel:[0,1] op_sel_hi:[1,0]
	v_pk_mov_b32 v[56:57], v[48:49], v[22:23] op_sel:[1,0]
	v_mov_b32_e32 v49, v23
	v_pk_add_f32 v[48:49], v[56:57], v[48:49]
	s_waitcnt vmcnt(9)
	v_lshlrev_b32_e32 v22, 16, v60
	v_and_b32_e32 v23, 0xffff0000, v60
	v_lshlrev_b32_e32 v56, 16, v61
	v_and_b32_e32 v57, 0xffff0000, v61
	s_waitcnt vmcnt(8)
	v_lshlrev_b32_e32 v58, 16, v72
	v_and_b32_e32 v59, 0xffff0000, v72
	v_lshlrev_b32_e32 v60, 16, v73
	v_and_b32_e32 v61, 0xffff0000, v73
	v_pk_add_f32 v[60:61], v[56:57], v[60:61]
	v_pk_add_f32 v[62:63], v[22:23], v[58:59]
	s_waitcnt vmcnt(7)
	v_lshlrev_b32_e32 v56, 16, v74
	v_and_b32_e32 v57, 0xffff0000, v74
	v_lshlrev_b32_e32 v22, 16, v75
	v_and_b32_e32 v23, 0xffff0000, v75
	global_load_dwordx4 v[72:75], v69, s[2:3]
	s_waitcnt vmcnt(7)
	v_lshlrev_b32_e32 v58, 16, v46
	v_and_b32_e32 v59, 0xffff0000, v46
	v_lshlrev_b32_e32 v46, 16, v47
	v_and_b32_e32 v47, 0xffff0000, v47
	v_pk_add_f32 v[22:23], v[22:23], v[46:47]
	v_pk_add_f32 v[46:47], v[56:57], v[58:59]
	v_pk_add_f32 v[48:49], v[48:49], v[48:49] op_sel:[0,1] op_sel_hi:[1,0]
	v_mul_f32_e32 v56, v46, v46
	v_mul_f32_e32 v57, v47, v47
	v_mov_b32_e32 v55, v56
	v_mov_b32_e32 v49, v57
	v_pk_add_f32 v[48:49], v[54:55], v[48:49]
	v_mul_f32_e32 v54, v63, v63
	v_mul_f32_e32 v56, v61, v61
	v_mul_f32_e32 v58, v22, v22
	v_mul_f32_e32 v59, v23, v23
	v_pk_fma_f32 v[54:55], v[62:63], v[62:63], v[54:55] op_sel_hi:[1,1,0]
	v_pk_fma_f32 v[56:57], v[60:61], v[60:61], v[56:57] op_sel_hi:[1,1,0]
	v_mov_b32_e32 v55, v58
	v_mov_b32_e32 v57, v59
	v_pk_add_f32 v[54:55], v[54:55], v[56:57]
	s_waitcnt vmcnt(5)
	v_lshlrev_b32_e32 v58, 16, v78
	v_pk_add_f32 v[84:85], v[48:49], v[54:55]
	v_lshlrev_b32_e32 v48, 16, v52
	v_and_b32_e32 v49, 0xffff0000, v52
	v_lshlrev_b32_e32 v54, 16, v53
	v_and_b32_e32 v55, 0xffff0000, v53
	s_waitcnt vmcnt(4)
	v_lshlrev_b32_e32 v52, 16, v50
	v_and_b32_e32 v53, 0xffff0000, v50
	v_lshlrev_b32_e32 v50, 16, v51
	v_and_b32_e32 v51, 0xffff0000, v51
	v_pk_add_f32 v[52:53], v[48:49], v[52:53]
	v_pk_add_f32 v[54:55], v[54:55], v[50:51]
	v_pk_mul_f32 v[50:51], v[52:53], v[52:53]
	v_pk_mul_f32 v[48:49], v[54:55], v[54:55]
	v_and_b32_e32 v59, 0xffff0000, v78
	v_pk_mov_b32 v[56:57], v[50:51], v[48:49] op_sel:[1,0]
	v_mov_b32_e32 v51, v49
	v_pk_add_f32 v[88:89], v[56:57], v[50:51]
	s_waitcnt vmcnt(3)
	v_lshlrev_b32_e32 v50, 16, v77
	v_and_b32_e32 v51, 0xffff0000, v77
	v_lshlrev_b32_e32 v56, 16, v79
	v_and_b32_e32 v57, 0xffff0000, v79
	v_lshlrev_b32_e32 v48, 16, v76
	v_and_b32_e32 v49, 0xffff0000, v76
	v_pk_add_f32 v[56:57], v[50:51], v[56:57]
	s_waitcnt vmcnt(2)
	v_lshlrev_b32_e32 v50, 16, v80
	v_and_b32_e32 v51, 0xffff0000, v80
	s_waitcnt vmcnt(1)
	v_lshlrev_b32_e32 v76, 16, v82
	v_and_b32_e32 v77, 0xffff0000, v82
	v_pk_add_f32 v[58:59], v[48:49], v[58:59]
	v_lshlrev_b32_e32 v48, 16, v81
	v_and_b32_e32 v49, 0xffff0000, v81
	v_lshlrev_b32_e32 v78, 16, v83
	v_and_b32_e32 v79, 0xffff0000, v83
	v_pk_add_f32 v[50:51], v[50:51], v[76:77]
	v_pk_add_f32 v[48:49], v[48:49], v[78:79]
	v_mul_f32_e32 v78, v50, v50
	v_pk_add_f32 v[76:77], v[84:85], v[84:85] op_sel:[0,1] op_sel_hi:[1,0]
	v_mul_f32_e32 v80, v51, v51
	v_mov_b32_e32 v77, v78
	v_pk_add_f32 v[78:79], v[88:89], v[88:89] op_sel:[0,1] op_sel_hi:[1,0]
	v_mul_f32_e32 v81, v48, v48
	v_mov_b32_e32 v79, v80
	v_pk_add_f32 v[76:77], v[76:77], v[78:79]
	v_mul_f32_e32 v78, v59, v59
	v_pk_fma_f32 v[78:79], v[58:59], v[58:59], v[78:79] op_sel_hi:[1,1,0]
	v_mul_f32_e32 v80, v57, v57
	v_mul_f32_e32 v82, v49, v49
	v_mov_b32_e32 v79, v81
	v_pk_fma_f32 v[80:81], v[56:57], v[56:57], v[80:81] op_sel_hi:[1,1,0]
	v_and_b32_e32 v83, 0xffff0000, v87
	v_mov_b32_e32 v81, v82
	v_pk_add_f32 v[78:79], v[78:79], v[80:81]
	v_lshlrev_b32_e32 v80, 16, v86
	v_pk_add_f32 v[76:77], v[76:77], v[78:79]
	v_and_b32_e32 v81, 0xffff0000, v86
	v_add_f32_e32 v76, v76, v77
	ds_bpermute_b32 v71, v71, v76
	v_xor_b32_e32 v77, 32, v68
	v_cmp_lt_i32_e32 vcc, v77, v70
	v_lshlrev_b32_e32 v82, 16, v87
	s_waitcnt lgkmcnt(0)
	v_add_f32_e32 v70, v76, v71
	v_cndmask_b32_e32 v68, v68, v77, vcc
	v_lshlrev_b32_e32 v68, 2, v68
	ds_bpermute_b32 v68, v68, v70
	s_waitcnt lgkmcnt(0)
; __device__ __forceinline__ f32x4 ld_bf4(const bf16_t* p) { u32x2 w = *(const u32x2*)p; return (f32x4){__uint_as_float(w.x << 16), __uint_as_float(w.x & 0xffff0000u), __uint_as_float(w.y << 16), __uint_as_float(w.y & 0xffff0000u)}; }
; __device__ __forceinline__ void st_bf4(bf16_t* p, f32x4 v) { u32x2 w; w.x = pk2(v[0], v[1]); w.y = pk2(v[2], v[3]); *(u32x2*)p = w; }
; __global__ void __launch_bounds__(NTHR, 2) fwd_kernel(Args a) {
;     ...
;         ss += __shfl_xor(ss, 16); ss += __shfl_xor(ss, 32);
;         const float rstd = rsqrtf(ss * (1.0f / DV) + EPS);
;         const size_t ro = (size_t)(b * SEQ + n * 64 + 16 * ct + fr) * VW + h * DV + 4 * fq;
; #pragma unroll
;         for (int t = 0; t < 16; ++t) { const f32x4 gg = *(const f32x4*)(a.in[I_GGLA] + h * DV + t * 16 + 4 * fq);
;             st_bf4(AG + ro + t * 16, ld_bf4(Rb + ro + t * 16) * (ov[t] * rstd * gg)); }
	v_add_f32_e32 v68, v70, v68
	v_mov_b32_e32 v70, 0x358637bd
	v_fmac_f32_e32 v70, 0x3b800000, v68
	v_mul_f32_e32 v68, 0x4b800000, v70
	v_cmp_gt_f32_e32 vcc, s4, v70
	s_nop 1
	v_cndmask_b32_e32 v68, v70, v68, vcc
	v_rsq_f32_e32 v68, v68
	s_nop 0
	v_mul_f32_e32 v70, 0x45800000, v68
	v_cndmask_b32_e32 v68, v68, v70, vcc
	v_pk_mul_f32 v[4:5], v[68:69], v[4:5] op_sel_hi:[0,1]
	v_pk_mul_f32 v[2:3], v[68:69], v[2:3] op_sel_hi:[0,1]
	global_load_dwordx2 v[96:97], v[0:1], off offset:32
	global_load_dwordx2 v[98:99], v[0:1], off offset:64
	global_load_dwordx2 v[100:101], v[0:1], off offset:96
	global_load_dwordx4 v[102:105], v69, s[2:3] offset:64
	global_load_dwordx4 v[106:109], v69, s[2:3] offset:128
	global_load_dwordx4 v[110:113], v69, s[2:3] offset:192
	global_load_dwordx2 v[114:115], v[0:1], off offset:128
	global_load_dwordx4 v[116:119], v69, s[2:3] offset:256
	global_load_dwordx2 v[120:121], v[0:1], off offset:160
	global_load_dwordx2 v[122:123], v[0:1], off offset:192
	global_load_dwordx2 v[124:125], v[0:1], off offset:224
	global_load_dwordx4 v[126:129], v69, s[2:3] offset:320
	global_load_dwordx4 v[130:133], v69, s[2:3] offset:384
	global_load_dwordx4 v[134:137], v69, s[2:3] offset:448
	global_load_dwordx2 v[138:139], v[0:1], off offset:256
	global_load_dwordx4 v[140:143], v69, s[2:3] offset:512
	global_load_dwordx2 v[144:145], v[0:1], off offset:288
	global_load_dwordx2 v[146:147], v[0:1], off offset:320
	global_load_dwordx2 v[148:149], v[0:1], off offset:352
	global_load_dwordx4 v[150:153], v69, s[2:3] offset:576
	global_load_dwordx4 v[154:157], v69, s[2:3] offset:640
	global_load_dwordx4 v[158:161], v69, s[2:3] offset:704
	global_load_dwordx2 v[162:163], v[0:1], off offset:384
	global_load_dwordx4 v[164:167], v69, s[2:3] offset:768
	global_load_dwordx2 v[168:169], v[0:1], off offset:416
	global_load_dwordx2 v[170:171], v[0:1], off offset:448
	global_load_dwordx2 v[172:173], v[0:1], off offset:480
	global_load_dwordx4 v[174:177], v69, s[2:3] offset:832
	global_load_dwordx4 v[178:181], v69, s[2:3] offset:896
	global_load_dwordx4 v[182:185], v69, s[2:3] offset:960
	s_waitcnt vmcnt(0)
	v_pk_mul_f32 v[2:3], v[72:73], v[2:3]
	v_pk_mul_f32 v[4:5], v[74:75], v[4:5]
	v_pk_mul_f32 v[2:3], v[2:3], v[80:81]
	v_pk_mul_f32 v[4:5], v[4:5], v[82:83]
	v_cvt_pk_bf16_f32 v2, v2, v3
	v_cvt_pk_bf16_f32 v3, v4, v5
	v_pk_mul_f32 v[8:9], v[68:69], v[8:9] op_sel_hi:[0,1]
	global_store_dwordx2 v[24:25], v[2:3], off
	v_pk_mul_f32 v[6:7], v[68:69], v[6:7] op_sel_hi:[0,1]
	v_pk_mul_f32 v[18:19], v[68:69], v[18:19] op_sel_hi:[0,1]
	v_pk_mul_f32 v[20:21], v[68:69], v[20:21] op_sel_hi:[0,1]
	v_pk_mul_f32 v[10:11], v[68:69], v[10:11] op_sel_hi:[0,1]
	v_pk_mul_f32 v[12:13], v[68:69], v[12:13] op_sel_hi:[0,1]
	v_pk_mul_f32 v[16:17], v[68:69], v[16:17] op_sel_hi:[0,1]
	v_pk_mul_f32 v[14:15], v[68:69], v[14:15] op_sel_hi:[0,1]
	s_nop 0
	v_lshlrev_b32_e32 v72, 16, v96
	v_and_b32_e32 v73, 0xffff0000, v96
	v_lshlrev_b32_e32 v70, 16, v97
	v_and_b32_e32 v71, 0xffff0000, v97
	s_nop 0
	v_pk_mul_f32 v[2:3], v[102:103], v[6:7]
	v_pk_mul_f32 v[4:5], v[104:105], v[8:9]
	v_pk_mul_f32 v[2:3], v[2:3], v[72:73]
	v_pk_mul_f32 v[4:5], v[4:5], v[70:71]
	v_cvt_pk_bf16_f32 v2, v2, v3
	v_cvt_pk_bf16_f32 v3, v4, v5
	global_store_dwordx2 v[24:25], v[2:3], off offset:32
	v_lshlrev_b32_e32 v6, 16, v98
	v_and_b32_e32 v7, 0xffff0000, v98
	v_lshlrev_b32_e32 v8, 16, v99
	v_and_b32_e32 v9, 0xffff0000, v99
	s_nop 0
	v_pk_mul_f32 v[2:3], v[106:107], v[20:21]
	v_pk_mul_f32 v[4:5], v[108:109], v[18:19]
	v_pk_mul_f32 v[2:3], v[2:3], v[6:7]
	v_pk_mul_f32 v[4:5], v[4:5], v[8:9]
	v_cvt_pk_bf16_f32 v2, v2, v3
	v_cvt_pk_bf16_f32 v3, v4, v5
	global_store_dwordx2 v[24:25], v[2:3], off offset:64
	v_lshlrev_b32_e32 v6, 16, v100
	v_and_b32_e32 v7, 0xffff0000, v100
	v_lshlrev_b32_e32 v8, 16, v101
	v_and_b32_e32 v9, 0xffff0000, v101
	s_nop 0
	v_pk_mul_f32 v[2:3], v[110:111], v[12:13]
	v_pk_mul_f32 v[4:5], v[112:113], v[10:11]
	v_pk_mul_f32 v[4:5], v[4:5], v[8:9]
	v_pk_mul_f32 v[2:3], v[2:3], v[6:7]
	s_nop 0
	v_lshlrev_b32_e32 v18, 16, v114
	v_cvt_pk_bf16_f32 v2, v2, v3
	v_cvt_pk_bf16_f32 v3, v4, v5
	global_store_dwordx2 v[24:25], v[2:3], off offset:96
	s_nop 0
	v_and_b32_e32 v19, 0xffff0000, v114
	v_lshlrev_b32_e32 v10, 16, v115
	v_and_b32_e32 v11, 0xffff0000, v115
	s_nop 0
	v_pk_mul_f32 v[2:3], v[116:117], v[14:15]
	v_pk_mul_f32 v[4:5], v[118:119], v[16:17]
	v_pk_mul_f32 v[2:3], v[2:3], v[18:19]
	v_pk_mul_f32 v[4:5], v[4:5], v[10:11]
	v_cvt_pk_bf16_f32 v2, v2, v3
	v_cvt_pk_bf16_f32 v3, v4, v5
	global_store_dwordx2 v[24:25], v[2:3], off offset:128
	v_pk_mul_f32 v[14:15], v[68:69], v[30:31] op_sel_hi:[0,1]
	v_pk_mul_f32 v[16:17], v[68:69], v[32:33] op_sel_hi:[0,1]
	s_nop 0
	v_lshlrev_b32_e32 v10, 16, v120
	v_and_b32_e32 v11, 0xffff0000, v120
	v_lshlrev_b32_e32 v6, 16, v121
	v_and_b32_e32 v7, 0xffff0000, v121
	v_pk_mul_f32 v[18:19], v[68:69], v[40:41] op_sel_hi:[0,1]
	s_nop 0
	v_pk_mul_f32 v[2:3], v[126:127], v[16:17]
	v_pk_mul_f32 v[4:5], v[128:129], v[14:15]
	v_pk_mul_f32 v[2:3], v[2:3], v[10:11]
	v_pk_mul_f32 v[4:5], v[4:5], v[6:7]
	v_cvt_pk_bf16_f32 v2, v2, v3
	v_cvt_pk_bf16_f32 v3, v4, v5
	global_store_dwordx2 v[24:25], v[2:3], off offset:160
	v_pk_mul_f32 v[10:11], v[68:69], v[26:27] op_sel_hi:[0,1]
	v_pk_mul_f32 v[14:15], v[68:69], v[28:29] op_sel_hi:[0,1]
; __device__ __forceinline__ f32x4 ld_bf4(const bf16_t* p) { u32x2 w = *(const u32x2*)p; return (f32x4){__uint_as_float(w.x << 16), __uint_as_float(w.x & 0xffff0000u), __uint_as_float(w.y << 16), __uint_as_float(w.y & 0xffff0000u)}; }
; __device__ __forceinline__ void st_bf4(bf16_t* p, f32x4 v) { u32x2 w; w.x = pk2(v[0], v[1]); w.y = pk2(v[2], v[3]); *(u32x2*)p = w; }
; __global__ void __launch_bounds__(NTHR, 2) fwd_kernel(Args a) {
;     ...
;         const size_t ro = (size_t)(b * SEQ + n * 64 + 16 * ct + fr) * VW + h * DV + 4 * fq;
; #pragma unroll
;         for (int t = 0; t < 16; ++t) { const f32x4 gg = *(const f32x4*)(a.in[I_GGLA] + h * DV + t * 16 + 4 * fq);
;             st_bf4(AG + ro + t * 16, ld_bf4(Rb + ro + t * 16) * (ov[t] * rstd * gg)); }
	v_lshlrev_b32_e32 v6, 16, v122
	v_and_b32_e32 v7, 0xffff0000, v122
	v_lshlrev_b32_e32 v8, 16, v123
	v_and_b32_e32 v9, 0xffff0000, v123
	v_pk_mul_f32 v[16:17], v[68:69], v[38:39] op_sel_hi:[0,1]
	s_nop 0
	v_pk_mul_f32 v[2:3], v[130:131], v[14:15]
	v_pk_mul_f32 v[4:5], v[132:133], v[10:11]
	v_pk_mul_f32 v[2:3], v[2:3], v[6:7]
	v_pk_mul_f32 v[4:5], v[4:5], v[8:9]
	v_cvt_pk_bf16_f32 v2, v2, v3
	v_cvt_pk_bf16_f32 v3, v4, v5
	global_store_dwordx2 v[24:25], v[2:3], off offset:192
	s_nop 0
	v_lshlrev_b32_e32 v8, 16, v124
	v_and_b32_e32 v9, 0xffff0000, v124
	v_lshlrev_b32_e32 v10, 16, v125
	v_and_b32_e32 v11, 0xffff0000, v125
	v_pk_mul_f32 v[12:13], v[68:69], v[44:45] op_sel_hi:[0,1]
	v_pk_mul_f32 v[14:15], v[68:69], v[42:43] op_sel_hi:[0,1]
	s_nop 0
	v_pk_mul_f32 v[2:3], v[134:135], v[14:15]
	v_pk_mul_f32 v[4:5], v[136:137], v[12:13]
	v_pk_mul_f32 v[2:3], v[2:3], v[8:9]
	v_pk_mul_f32 v[4:5], v[4:5], v[10:11]
	v_cvt_pk_bf16_f32 v2, v2, v3
	v_cvt_pk_bf16_f32 v3, v4, v5
	global_store_dwordx2 v[24:25], v[2:3], off offset:224
	s_nop 0
	s_nop 0
	v_lshlrev_b32_e32 v14, 16, v138
	v_and_b32_e32 v15, 0xffff0000, v138
	v_lshlrev_b32_e32 v6, 16, v139
	v_and_b32_e32 v7, 0xffff0000, v139
	s_nop 0
	v_pk_mul_f32 v[2:3], v[140:141], v[18:19]
	v_pk_mul_f32 v[4:5], v[142:143], v[16:17]
	v_pk_mul_f32 v[2:3], v[2:3], v[14:15]
	v_pk_mul_f32 v[4:5], v[4:5], v[6:7]
	v_cvt_pk_bf16_f32 v2, v2, v3
	v_cvt_pk_bf16_f32 v3, v4, v5
	global_store_dwordx2 v[24:25], v[2:3], off offset:256
	v_pk_mul_f32 v[14:15], v[68:69], v[34:35] op_sel_hi:[0,1]
	v_pk_mul_f32 v[16:17], v[68:69], v[36:37] op_sel_hi:[0,1]
	s_nop 0
	v_lshlrev_b32_e32 v6, 16, v144
	v_and_b32_e32 v7, 0xffff0000, v144
	v_lshlrev_b32_e32 v8, 16, v145
	v_and_b32_e32 v9, 0xffff0000, v145
	s_nop 0
	v_pk_mul_f32 v[2:3], v[150:151], v[16:17]
	v_pk_mul_f32 v[4:5], v[152:153], v[14:15]
	v_pk_mul_f32 v[2:3], v[2:3], v[6:7]
	v_pk_mul_f32 v[4:5], v[4:5], v[8:9]
	v_cvt_pk_bf16_f32 v2, v2, v3
	v_cvt_pk_bf16_f32 v3, v4, v5
	global_store_dwordx2 v[24:25], v[2:3], off offset:288
	v_lshlrev_b32_e32 v6, 16, v146
	v_and_b32_e32 v7, 0xffff0000, v146
	v_lshlrev_b32_e32 v8, 16, v147
	v_and_b32_e32 v9, 0xffff0000, v147
	v_pk_mul_f32 v[10:11], v[68:69], v[66:67] op_sel_hi:[0,1]
	v_pk_mul_f32 v[14:15], v[68:69], v[64:65] op_sel_hi:[0,1]
	v_pk_mul_f32 v[16:17], v[68:69], v[46:47] op_sel_hi:[0,1]
	s_nop 0
	v_pk_mul_f32 v[2:3], v[154:155], v[14:15]
	v_pk_mul_f32 v[4:5], v[156:157], v[10:11]
	v_pk_mul_f32 v[2:3], v[2:3], v[6:7]
	v_pk_mul_f32 v[4:5], v[4:5], v[8:9]
	v_cvt_pk_bf16_f32 v2, v2, v3
	v_cvt_pk_bf16_f32 v3, v4, v5
	global_store_dwordx2 v[24:25], v[2:3], off offset:320
	s_nop 0
	v_lshlrev_b32_e32 v8, 16, v148
	v_and_b32_e32 v9, 0xffff0000, v148
	v_lshlrev_b32_e32 v10, 16, v149
	v_and_b32_e32 v11, 0xffff0000, v149
	v_pk_mul_f32 v[12:13], v[68:69], v[60:61] op_sel_hi:[0,1]
	v_pk_mul_f32 v[14:15], v[68:69], v[62:63] op_sel_hi:[0,1]
	s_nop 0
	v_pk_mul_f32 v[2:3], v[158:159], v[14:15]
	v_pk_mul_f32 v[4:5], v[160:161], v[12:13]
	v_pk_mul_f32 v[2:3], v[2:3], v[8:9]
	v_pk_mul_f32 v[4:5], v[4:5], v[10:11]
	v_cvt_pk_bf16_f32 v2, v2, v3
	v_cvt_pk_bf16_f32 v3, v4, v5
	global_store_dwordx2 v[24:25], v[2:3], off offset:352
	s_nop 0
	v_pk_mul_f32 v[14:15], v[68:69], v[22:23] op_sel_hi:[0,1]
	s_nop 0
	v_lshlrev_b32_e32 v0, 16, v162
	v_and_b32_e32 v1, 0xffff0000, v162
	v_lshlrev_b32_e32 v6, 16, v163
	v_and_b32_e32 v7, 0xffff0000, v163
	s_nop 0
	v_pk_mul_f32 v[2:3], v[164:165], v[16:17]
	v_pk_mul_f32 v[4:5], v[166:167], v[14:15]
	v_pk_mul_f32 v[0:1], v[2:3], v[0:1]
	v_pk_mul_f32 v[4:5], v[4:5], v[6:7]
	v_cvt_pk_bf16_f32 v0, v0, v1
	v_cvt_pk_bf16_f32 v1, v4, v5
	global_store_dwordx2 v[24:25], v[0:1], off offset:384
	s_nop 0
	v_lshlrev_b32_e32 v4, 16, v168
	v_and_b32_e32 v5, 0xffff0000, v168
	v_lshlrev_b32_e32 v6, 16, v169
	v_and_b32_e32 v7, 0xffff0000, v169
	v_pk_mul_f32 v[8:9], v[68:69], v[54:55] op_sel_hi:[0,1]
	v_pk_mul_f32 v[14:15], v[68:69], v[52:53] op_sel_hi:[0,1]
	s_nop 0
	v_pk_mul_f32 v[0:1], v[174:175], v[14:15]
	v_pk_mul_f32 v[2:3], v[176:177], v[8:9]
	v_pk_mul_f32 v[0:1], v[0:1], v[4:5]
	v_pk_mul_f32 v[2:3], v[2:3], v[6:7]
	v_cvt_pk_bf16_f32 v0, v0, v1
	v_cvt_pk_bf16_f32 v1, v2, v3
	global_store_dwordx2 v[24:25], v[0:1], off offset:416
	v_lshlrev_b32_e32 v4, 16, v170
	v_and_b32_e32 v5, 0xffff0000, v170
	v_lshlrev_b32_e32 v6, 16, v171
	v_and_b32_e32 v7, 0xffff0000, v171
	v_pk_mul_f32 v[8:9], v[68:69], v[56:57] op_sel_hi:[0,1]
	v_pk_mul_f32 v[10:11], v[68:69], v[58:59] op_sel_hi:[0,1]
	s_nop 0
	v_pk_mul_f32 v[0:1], v[178:179], v[10:11]
	v_pk_mul_f32 v[2:3], v[180:181], v[8:9]
	v_pk_mul_f32 v[0:1], v[0:1], v[4:5]
	v_pk_mul_f32 v[2:3], v[2:3], v[6:7]
	v_cvt_pk_bf16_f32 v0, v0, v1
	v_cvt_pk_bf16_f32 v1, v2, v3
	global_store_dwordx2 v[24:25], v[0:1], off offset:448
	v_pk_mul_f32 v[8:9], v[68:69], v[48:49] op_sel_hi:[0,1]
	v_pk_mul_f32 v[10:11], v[68:69], v[50:51] op_sel_hi:[0,1]
	v_lshlrev_b32_e32 v4, 16, v172
	v_and_b32_e32 v5, 0xffff0000, v172
	v_lshlrev_b32_e32 v6, 16, v173
	v_and_b32_e32 v7, 0xffff0000, v173
	s_nop 0
	v_pk_mul_f32 v[0:1], v[182:183], v[10:11]
	v_pk_mul_f32 v[2:3], v[184:185], v[8:9]
	v_pk_mul_f32 v[0:1], v[0:1], v[4:5]
	v_pk_mul_f32 v[2:3], v[2:3], v[6:7]
	v_cvt_pk_bf16_f32 v0, v0, v1
	v_cvt_pk_bf16_f32 v1, v2, v3
	global_store_dwordx2 v[24:25], v[0:1], off offset:480
